# stack f + w_in GEMM epilogue: identity rotation (cos 1, sin 0, never the rope tile) deleted, conversions read the accumulators
# speedup vs baseline: 1.0015x; 1.0015x over previous
; __device__ __forceinline__ unsigned cvt_pk_bf16(float lo, float hi) { unsigned r; asm("v_cvt_pk_bf16_f32 %0, %1, %2" : "=v"(r) : "v"(lo), "v"(hi)); return r; }
;     __device__ __forceinline__ void operator()(AccRef acc, const pg8::Unit& u, int wr, int wc, int fr, int fq) const {
;         const int row0 = u.pm * 256 + wr * 64 + fr, col0 = u.pn * 256 + wc * 32 + 4 * fq;
;         const bool rope = (u.pn == rope_pn) && (u.pm < 32);
; #pragma unroll
;         for (int ai = 0; ai < 2; ++ai)
; #pragma unroll
;             for (int m = 0; m < 4; ++m) { const int row = row0 + ai * 128 + m * 16; bf16_t* rowp = O + (size_t)row * ldc + col0;
;                 f32x4 cs = {1.f, 1.f, 1.f, 1.f}, sn = {0.f, 0.f, 0.f, 0.f};
;                 if (rope) { const int t = row & 2047; const int pos = (wc & 1) ? (t & 63) : (t >> 6); cs = *(const f32x4*)(cos64 + pos * 16 + 4 * fq); sn = *(const f32x4*)(sin64 + pos * 16 + 4 * fq); }
; #pragma unroll
;                 for (int bj = 0; bj < 2; ++bj) {
;                     const f32x4 x0 = acc[ai][bj][m][0], x1 = acc[ai][bj][m][1];
;                     const f32x4 y0 = x0 * cs - x1 * sn, y1 = x1 * cs + x0 * sn;
;                     u32x2 w0, w1; w0.x = cvt_pk_bf16(y0[0], y0[1]); w0.y = cvt_pk_bf16(y0[2], y0[3]); w1.x = cvt_pk_bf16(y1[0], y1[1]); w1.y = cvt_pk_bf16(y1[2], y1[3]);
;                     *(u32x2*)(rowp + bj * 128) = w0; *(u32x2*)(rowp + bj * 128 + 16) = w1; } }
;     }
.LBB0_2717:
	v_add_u32_e32 v20, 0xb0, v157
	v_mov_b64_e32 v[18:19], s[74:75]
	v_mad_i64_i32 v[18:19], s[30:31], v20, s15, v[18:19]
	v_lshl_add_u64 v[18:19], v[142:143], 1, v[18:19]
	v_cvt_pk_bf16_f32 v12, v12, v13
	v_cvt_pk_bf16_f32 v13, v14, v15
	v_cvt_pk_bf16_f32 v8, v8, v9
	s_and_b64 vcc, exec, s[40:41]
	v_cvt_pk_bf16_f32 v9, v10, v11
	global_store_dwordx2 v[18:19], v[12:13], off
	global_store_dwordx2 v[18:19], v[8:9], off offset:32
	v_cvt_pk_bf16_f32 v4, v4, v5
	v_cvt_pk_bf16_f32 v5, v6, v7
	s_mov_b32 s55, s2
	s_mov_b32 s56, s10
	s_mov_b64 s[48:49], s[46:47]
	s_mov_b64 s[42:43], s[44:45]
	v_cvt_pk_bf16_f32 v0, v0, v1
	s_nop 0
	v_cvt_pk_bf16_f32 v1, v2, v3
	global_store_dwordx2 v[18:19], v[4:5], off offset:256
	global_store_dwordx2 v[18:19], v[0:1], off offset:288
	s_cbranch_vccnz .LBB0_2738

; __device__ __forceinline__ unsigned cvt_pk_bf16(float lo, float hi) { unsigned r; asm("v_cvt_pk_bf16_f32 %0, %1, %2" : "=v"(r) : "v"(lo), "v"(hi)); return r; }
;     __device__ __forceinline__ void operator()(AccRef acc, const pg8::Unit& u, int wr, int wc, int fr, int fq) const {
;         const int row0 = u.pm * 256 + wr * 64 + fr, col0 = u.pn * 256 + wc * 32 + 4 * fq;
;         const bool rope = (u.pn == rope_pn) && (u.pm < 32);
; #pragma unroll
;         for (int ai = 0; ai < 2; ++ai)
; #pragma unroll
;             for (int m = 0; m < 4; ++m) { const int row = row0 + ai * 128 + m * 16; bf16_t* rowp = O + (size_t)row * ldc + col0;
;                 f32x4 cs = {1.f, 1.f, 1.f, 1.f}, sn = {0.f, 0.f, 0.f, 0.f};
;                 if (rope) { const int t = row & 2047; const int pos = (wc & 1) ? (t & 63) : (t >> 6); cs = *(const f32x4*)(cos64 + pos * 16 + 4 * fq); sn = *(const f32x4*)(sin64 + pos * 16 + 4 * fq); }
; #pragma unroll
;                 for (int bj = 0; bj < 2; ++bj) {
;                     const f32x4 x0 = acc[ai][bj][m][0], x1 = acc[ai][bj][m][1];
;                     const f32x4 y0 = x0 * cs - x1 * sn, y1 = x1 * cs + x0 * sn;
;                     u32x2 w0, w1; w0.x = cvt_pk_bf16(y0[0], y0[1]); w0.y = cvt_pk_bf16(y0[2], y0[3]); w1.x = cvt_pk_bf16(y1[0], y1[1]); w1.y = cvt_pk_bf16(y1[2], y1[3]);
;                     *(u32x2*)(rowp + bj * 128) = w0; *(u32x2*)(rowp + bj * 128 + 16) = w1; } }
;     }
.LBB0_2724:
	v_or_b32_e32 v157, s11, v150
	v_lshl_or_b32 v142, s55, 8, v155
	v_mov_b64_e32 v[158:159], s[74:75]
	v_ashrrev_i32_e32 v143, 31, v142
	v_mad_i64_i32 v[158:159], s[30:31], v157, s15, v[158:159]
	v_lshl_add_u64 v[158:159], v[142:143], 1, v[158:159]
	v_cvt_pk_bf16_f32 v124, v124, v125
	v_cvt_pk_bf16_f32 v125, v126, v127
	v_cvt_pk_bf16_f32 v120, v120, v121
	v_cvt_pk_bf16_f32 v121, v122, v123
	global_store_dwordx2 v[158:159], v[124:125], off
	global_store_dwordx2 v[158:159], v[120:121], off offset:32
	v_cvt_pk_bf16_f32 v116, v116, v117
	v_cvt_pk_bf16_f32 v117, v118, v119
	v_cvt_pk_bf16_f32 v112, v112, v113
	s_and_b64 vcc, exec, s[42:43]
	v_cvt_pk_bf16_f32 v113, v114, v115
	global_store_dwordx2 v[158:159], v[116:117], off offset:256
	global_store_dwordx2 v[158:159], v[112:113], off offset:288
	v_mov_b32_e32 v129, 0
	v_mov_b32_e32 v130, 0
	v_mov_b32_e32 v131, 0
	v_mov_b32_e32 v145, 1.0
	v_mov_b32_e32 v112, 1.0
	v_mov_b32_e32 v113, 1.0
	s_cbranch_vccnz .LBB0_2726
	v_mov_b32_e32 v112, s3
	v_cndmask_b32_e64 v112, v152, v112, s[38:39]
	v_lshl_or_b32 v112, v112, 6, v136
	v_mov_b32_e32 v113, v137
	flat_load_dwordx4 v[128:131], v[112:113]
	s_waitcnt vmcnt(0) lgkmcnt(0)
	v_mov_b32_e32 v144, v128
	v_mov_b32_e32 v145, v129
	v_mov_b32_e32 v112, v130
	v_mov_b32_e32 v113, v131
.LBB0_2726:
	v_or_b32_e32 v116, 16, v157
	v_mov_b64_e32 v[114:115], s[74:75]
	v_mad_i64_i32 v[114:115], s[30:31], v116, s15, v[114:115]
	v_lshl_add_u64 v[114:115], v[142:143], 1, v[114:115]
	v_cvt_pk_bf16_f32 v108, v108, v109
	v_cvt_pk_bf16_f32 v109, v110, v111
	v_cvt_pk_bf16_f32 v104, v104, v105
	v_cvt_pk_bf16_f32 v105, v106, v107
	global_store_dwordx2 v[114:115], v[108:109], off
	global_store_dwordx2 v[114:115], v[104:105], off offset:32
	v_cvt_pk_bf16_f32 v100, v100, v101
	v_cvt_pk_bf16_f32 v101, v102, v103
	v_cvt_pk_bf16_f32 v96, v96, v97
	v_mov_b32_e32 v102, 1.0
	v_cvt_pk_bf16_f32 v97, v98, v99
	global_store_dwordx2 v[114:115], v[100:101], off offset:256
	global_store_dwordx2 v[114:115], v[96:97], off offset:288
	v_mov_b32_e32 v96, 0
	s_and_b64 vcc, exec, s[42:43]
	v_mov_b32_e32 v98, 0
	v_mov_b32_e32 v99, 0
	v_mov_b32_e32 v100, 0
	v_mov_b32_e32 v101, 0
	v_mov_b32_e32 v104, 1.0
	v_mov_b32_e32 v105, 1.0
	v_mov_b32_e32 v106, 1.0
	v_mov_b32_e32 v107, 1.0
	s_cbranch_vccnz .LBB0_2728
	v_mov_b32_e32 v97, s3
	v_cndmask_b32_e64 v97, v153, v97, s[38:39]
	v_lshl_or_b32 v98, v97, 6, v136
	v_mov_b32_e32 v99, v137
	flat_load_dwordx4 v[98:101], v[98:99]
	s_waitcnt vmcnt(0) lgkmcnt(0)
	v_mov_b32_e32 v104, v98
	v_mov_b32_e32 v105, v99
	v_mov_b32_e32 v106, v100
	v_mov_b32_e32 v107, v101
.LBB0_2728:
	v_or_b32_e32 v97, 32, v157
	v_mov_b64_e32 v[108:109], s[74:75]
	v_mad_i64_i32 v[108:109], s[30:31], v97, s15, v[108:109]
	v_lshl_add_u64 v[108:109], v[142:143], 1, v[108:109]
	v_cvt_pk_bf16_f32 v92, v92, v93
	v_cvt_pk_bf16_f32 v93, v94, v95
	v_cvt_pk_bf16_f32 v88, v88, v89
	v_cvt_pk_bf16_f32 v89, v90, v91
	global_store_dwordx2 v[108:109], v[92:93], off
	global_store_dwordx2 v[108:109], v[88:89], off offset:32
	v_cvt_pk_bf16_f32 v84, v84, v85
	v_cvt_pk_bf16_f32 v85, v86, v87
	v_cvt_pk_bf16_f32 v80, v80, v81
	s_and_b64 vcc, exec, s[42:43]
	v_cvt_pk_bf16_f32 v81, v82, v83
	global_store_dwordx2 v[108:109], v[84:85], off offset:256
	global_store_dwordx2 v[108:109], v[80:81], off offset:288
	v_mov_b32_e32 v97, 0
	v_mov_b32_e32 v98, 0
	v_mov_b32_e32 v99, 0
	v_mov_b32_e32 v103, 1.0
	v_mov_b32_e32 v80, 1.0
	v_mov_b32_e32 v81, 1.0
	s_cbranch_vccnz .LBB0_2730
	v_mov_b32_e32 v80, s3
	v_cndmask_b32_e64 v80, v154, v80, s[38:39]
	v_lshl_or_b32 v80, v80, 6, v136
	v_mov_b32_e32 v81, v137
	flat_load_dwordx4 v[96:99], v[80:81]
	s_waitcnt vmcnt(0) lgkmcnt(0)
	v_mov_b32_e32 v102, v96
	v_mov_b32_e32 v103, v97
	v_mov_b32_e32 v80, v98
	v_mov_b32_e32 v81, v99
; __device__ __forceinline__ unsigned cvt_pk_bf16(float lo, float hi) { unsigned r; asm("v_cvt_pk_bf16_f32 %0, %1, %2" : "=v"(r) : "v"(lo), "v"(hi)); return r; }
;     __device__ __forceinline__ void operator()(AccRef acc, const pg8::Unit& u, int wr, int wc, int fr, int fq) const {
;         const int row0 = u.pm * 256 + wr * 64 + fr, col0 = u.pn * 256 + wc * 32 + 4 * fq;
;         const bool rope = (u.pn == rope_pn) && (u.pm < 32);
; #pragma unroll
;         for (int ai = 0; ai < 2; ++ai)
; #pragma unroll
;             for (int m = 0; m < 4; ++m) { const int row = row0 + ai * 128 + m * 16; bf16_t* rowp = O + (size_t)row * ldc + col0;
;                 f32x4 cs = {1.f, 1.f, 1.f, 1.f}, sn = {0.f, 0.f, 0.f, 0.f};
;                 if (rope) { const int t = row & 2047; const int pos = (wc & 1) ? (t & 63) : (t >> 6); cs = *(const f32x4*)(cos64 + pos * 16 + 4 * fq); sn = *(const f32x4*)(sin64 + pos * 16 + 4 * fq); }
; #pragma unroll
;                 for (int bj = 0; bj < 2; ++bj) {
;                     const f32x4 x0 = acc[ai][bj][m][0], x1 = acc[ai][bj][m][1];
;                     const f32x4 y0 = x0 * cs - x1 * sn, y1 = x1 * cs + x0 * sn;
;                     u32x2 w0, w1; w0.x = cvt_pk_bf16(y0[0], y0[1]); w0.y = cvt_pk_bf16(y0[2], y0[3]); w1.x = cvt_pk_bf16(y1[0], y1[1]); w1.y = cvt_pk_bf16(y1[2], y1[3]);
;                     *(u32x2*)(rowp + bj * 128) = w0; *(u32x2*)(rowp + bj * 128 + 16) = w1; } }
;     }
.LBB0_2730:
	v_or_b32_e32 v84, 48, v157
	v_mov_b64_e32 v[82:83], s[74:75]
	v_mad_i64_i32 v[82:83], s[30:31], v84, s15, v[82:83]
	v_lshl_add_u64 v[82:83], v[142:143], 1, v[82:83]
	v_cvt_pk_bf16_f32 v76, v76, v77
	v_cvt_pk_bf16_f32 v77, v78, v79
	v_cvt_pk_bf16_f32 v72, v72, v73
	v_cvt_pk_bf16_f32 v73, v74, v75
	global_store_dwordx2 v[82:83], v[76:77], off
	global_store_dwordx2 v[82:83], v[72:73], off offset:32
	v_cvt_pk_bf16_f32 v68, v68, v69
	v_cvt_pk_bf16_f32 v69, v70, v71
	v_cvt_pk_bf16_f32 v64, v64, v65
	v_mov_b32_e32 v70, 1.0
	v_cvt_pk_bf16_f32 v65, v66, v67
	global_store_dwordx2 v[82:83], v[68:69], off offset:256
	global_store_dwordx2 v[82:83], v[64:65], off offset:288
	v_add_u32_e32 v65, 0x80, v157
	v_bfe_u32 v76, v65, 6, 5
	v_mov_b32_e32 v64, 0
	s_and_b64 vcc, exec, s[42:43]
	v_mov_b32_e32 v66, 0
	v_mov_b32_e32 v67, 0
	v_mov_b32_e32 v68, 0
	v_mov_b32_e32 v69, 0
	v_mov_b32_e32 v72, 1.0
	v_mov_b32_e32 v73, 1.0
	v_mov_b32_e32 v74, 1.0
	v_mov_b32_e32 v75, 1.0
	s_cbranch_vccnz .LBB0_2732
	v_cndmask_b32_e64 v66, v150, v76, s[38:39]
	v_lshl_or_b32 v66, v66, 6, v136
	v_mov_b32_e32 v67, v137
	flat_load_dwordx4 v[66:69], v[66:67]
	s_waitcnt vmcnt(0) lgkmcnt(0)
	v_mov_b32_e32 v72, v66
	v_mov_b32_e32 v73, v67
	v_mov_b32_e32 v74, v68
	v_mov_b32_e32 v75, v69
.LBB0_2732:
	v_mov_b64_e32 v[78:79], s[74:75]
	v_mad_i64_i32 v[78:79], s[30:31], v65, s15, v[78:79]
	v_lshl_add_u64 v[78:79], v[142:143], 1, v[78:79]
	v_cvt_pk_bf16_f32 v60, v60, v61
	v_cvt_pk_bf16_f32 v61, v62, v63
	v_cvt_pk_bf16_f32 v56, v56, v57
	v_cvt_pk_bf16_f32 v57, v58, v59
	global_store_dwordx2 v[78:79], v[60:61], off
	global_store_dwordx2 v[78:79], v[56:57], off offset:32
	v_cvt_pk_bf16_f32 v52, v52, v53
	v_cvt_pk_bf16_f32 v53, v54, v55
	v_cvt_pk_bf16_f32 v48, v48, v49
	s_and_b64 vcc, exec, s[42:43]
	v_cvt_pk_bf16_f32 v49, v50, v51
	global_store_dwordx2 v[78:79], v[52:53], off offset:256
	global_store_dwordx2 v[78:79], v[48:49], off offset:288
	v_mov_b32_e32 v65, 0
	v_mov_b32_e32 v66, 0
	v_mov_b32_e32 v67, 0
	v_mov_b32_e32 v71, 1.0
	v_mov_b32_e32 v48, 1.0
	v_mov_b32_e32 v49, 1.0
	s_cbranch_vccnz .LBB0_2734
	v_cndmask_b32_e64 v48, v152, v76, s[38:39]
	v_lshl_or_b32 v48, v48, 6, v136
	v_mov_b32_e32 v49, v137
	flat_load_dwordx4 v[64:67], v[48:49]
	s_waitcnt vmcnt(0) lgkmcnt(0)
	v_mov_b32_e32 v70, v64
	v_mov_b32_e32 v71, v65
	v_mov_b32_e32 v48, v66
	v_mov_b32_e32 v49, v67
.LBB0_2734:
	v_add_u32_e32 v52, 0x90, v157
	v_mov_b64_e32 v[50:51], s[74:75]
	v_mad_i64_i32 v[50:51], s[30:31], v52, s15, v[50:51]
	v_lshl_add_u64 v[50:51], v[142:143], 1, v[50:51]
	v_cvt_pk_bf16_f32 v44, v44, v45
	v_cvt_pk_bf16_f32 v45, v46, v47
	v_cvt_pk_bf16_f32 v40, v40, v41
	v_cvt_pk_bf16_f32 v41, v42, v43
	global_store_dwordx2 v[50:51], v[44:45], off
	global_store_dwordx2 v[50:51], v[40:41], off offset:32
	v_cvt_pk_bf16_f32 v36, v36, v37
	v_cvt_pk_bf16_f32 v37, v38, v39
	v_cvt_pk_bf16_f32 v32, v32, v33
	v_mov_b32_e32 v38, 1.0
	v_cvt_pk_bf16_f32 v33, v34, v35
	global_store_dwordx2 v[50:51], v[36:37], off offset:256
	global_store_dwordx2 v[50:51], v[32:33], off offset:288
	v_mov_b32_e32 v32, 0
	s_and_b64 vcc, exec, s[42:43]
	v_mov_b32_e32 v34, 0
	v_mov_b32_e32 v35, 0
	v_mov_b32_e32 v36, 0
	v_mov_b32_e32 v37, 0
	v_mov_b32_e32 v40, 1.0
	v_mov_b32_e32 v41, 1.0
	v_mov_b32_e32 v42, 1.0
	v_mov_b32_e32 v43, 1.0
	s_cbranch_vccnz .LBB0_2736
	v_cndmask_b32_e64 v33, v153, v76, s[38:39]
	v_lshl_or_b32 v34, v33, 6, v136
	v_mov_b32_e32 v35, v137
	flat_load_dwordx4 v[34:37], v[34:35]
	s_waitcnt vmcnt(0) lgkmcnt(0)
	v_mov_b32_e32 v40, v34
	v_mov_b32_e32 v41, v35
	v_mov_b32_e32 v42, v36
	v_mov_b32_e32 v43, v37
.LBB0_2736:
	v_add_u32_e32 v33, 0xa0, v157
	v_mov_b64_e32 v[44:45], s[74:75]
	v_mad_i64_i32 v[44:45], s[30:31], v33, s15, v[44:45]
	v_lshl_add_u64 v[44:45], v[142:143], 1, v[44:45]
	v_cvt_pk_bf16_f32 v28, v28, v29
	v_cvt_pk_bf16_f32 v29, v30, v31
	v_cvt_pk_bf16_f32 v24, v24, v25
	v_cvt_pk_bf16_f32 v25, v26, v27
	global_store_dwordx2 v[44:45], v[28:29], off
	global_store_dwordx2 v[44:45], v[24:25], off offset:32
	v_cvt_pk_bf16_f32 v20, v20, v21
	v_cvt_pk_bf16_f32 v21, v22, v23
	v_cvt_pk_bf16_f32 v16, v16, v17
	s_and_b64 vcc, exec, s[42:43]
	v_cvt_pk_bf16_f32 v17, v18, v19
	global_store_dwordx2 v[44:45], v[20:21], off offset:256
	global_store_dwordx2 v[44:45], v[16:17], off offset:288
	v_mov_b32_e32 v33, 0
	v_mov_b32_e32 v34, 0
	v_mov_b32_e32 v35, 0
	v_mov_b32_e32 v39, 1.0
	v_mov_b32_e32 v16, 1.0
	v_mov_b32_e32 v17, 1.0
	s_cbranch_vccnz .LBB0_2717
	v_cndmask_b32_e64 v16, v154, v76, s[38:39]
	v_lshl_or_b32 v16, v16, 6, v136
	v_mov_b32_e32 v17, v137
	flat_load_dwordx4 v[32:35], v[16:17]
	s_waitcnt vmcnt(0) lgkmcnt(0)
	v_mov_b32_e32 v38, v32
	v_mov_b32_e32 v39, v33
	v_mov_b32_e32 v16, v34
	v_mov_b32_e32 v17, v35
	s_branch .LBB0_2717
